# v70 plus load batching in three more latency chains: sample-attention 41st tile, sample-mLSTM state update, silu(c_prompt) at kernel start
# speedup vs baseline: 1.0125x; 1.0029x over previous
.LBB0_11:
	s_or_b64 exec, exec, s[4:5]
	v_and_b32_e32 v232, 63, v0
	s_mov_b64 s[6:7], s[0:1]
	v_mov_b32_e32 v82, v0
	s_mov_b64 s[8:9], s[44:45]
	v_mov_b32_e32 v4, v232
	s_mov_b64 s[4:5], s[46:47]
	s_load_dwordx8 s[8:15], s[6:7], 0x40
	s_movk_i32 s3, 0x800
	v_cmp_gt_i32_e32 vcc, s3, v82
	s_and_saveexec_b64 s[6:7], vcc
	s_cbranch_execz .LBB0_14
	s_waitcnt lgkmcnt(0)
	v_lshlrev_b32_e32 v2, 2, v82
	v_add_u32_e32 v3, 0x1000, v2
	global_load_dword v6, v2, s[8:9]
	global_load_dword v7, v2, s[8:9] offset:2048
	global_load_dword v8, v3, s[8:9]
	global_load_dword v9, v3, s[8:9] offset:2048
	v_add_u32_e32 v5, 0x10000, v2
	v_ashrrev_i32_e32 v83, 31, v82
	s_waitcnt vmcnt(0)
	v_mul_f32_e32 v10, 0xbfb8aa3b, v6
	v_mul_f32_e32 v11, 0xbfb8aa3b, v7
	v_mul_f32_e32 v12, 0xbfb8aa3b, v8
	v_mul_f32_e32 v13, 0xbfb8aa3b, v9
	v_exp_f32_e32 v10, v10
	v_exp_f32_e32 v11, v11
	v_exp_f32_e32 v12, v12
	v_exp_f32_e32 v13, v13
	v_add_f32_e32 v10, 1.0, v10
	v_add_f32_e32 v11, 1.0, v11
	v_add_f32_e32 v12, 1.0, v12
	v_add_f32_e32 v13, 1.0, v13
	v_rcp_f32_e32 v10, v10
	v_rcp_f32_e32 v11, v11
	v_rcp_f32_e32 v12, v12
	v_rcp_f32_e32 v13, v13
	v_mul_f32_e32 v6, v6, v10
	v_mul_f32_e32 v7, v7, v11
	v_mul_f32_e32 v8, v8, v12
	v_mul_f32_e32 v9, v9, v13
	ds_write_b32 v5, v6
	ds_write_b32 v5, v7 offset:2048
	ds_write_b32 v5, v8 offset:4096
	ds_write_b32 v5, v9 offset:6144

.LBB0_810:
	s_and_b64 vcc, exec, s[10:11]
	s_mov_b32 s18, s54
	s_cbranch_vccz .LBB0_812
	s_nop 8
	v_lshl_add_u64 v[66:67], v[238:239], 0, s[70:71]
	v_lshl_add_u64 v[66:67], v[236:237], 1, v[66:67]
	v_lshl_add_u64 v[74:75], v[66:67], 0, s[6:7]
	v_add_co_u32_e32 v66, vcc, 0x2000, v66
	v_ashrrev_i32_e32 v71, 4, v235
	v_lshlrev_b32_e32 v70, 4, v235
	v_addc_co_u32_e32 v67, vcc, 0, v67, vcc
	v_and_b32_e32 v72, 0xf0, v70
	v_mov_b32_e32 v73, v83
	v_and_or_b32 v76, v71, 7, s97
	v_mul_lo_u32 v82, v76, s48
	v_add_u32_e32 v70, s94, v72
	v_lshl_add_u64 v[192:193], v[82:83], 1, s[84:85]
	v_lshl_add_u64 v[192:193], v[192:193], 0, s[70:71]
	v_lshl_add_u64 v[192:193], v[192:193], 0, v[72:73]
	v_add_co_u32_e32 v192, vcc, s67, v192
	v_mad_u64_u32 v[78:79], s[10:11], v71, s5, v[70:71]
	s_mov_b64 s[12:13], 0xc000
	v_addc_co_u32_e32 v193, vcc, 0, v193, vcc
	v_mov_b32_e32 v196, 0
	v_lshl_add_u64 v[194:195], v[192:193], 0, s[12:13]
	global_load_dwordx4 v[66:69], v[66:67], off
	global_load_dwordx4 v[112:115], v[74:75], off offset:32
	global_load_dwordx4 v[104:107], v[74:75], off offset:64
	global_load_dwordx4 v[96:99], v[74:75], off offset:96
	global_load_dwordx4 v[100:103], v[74:75], off offset:128
	global_load_dwordx4 v[92:95], v[74:75], off offset:160
	global_load_dwordx4 v[88:91], v[74:75], off offset:192
	global_load_dwordx4 v[84:87], v[74:75], off offset:224
	global_load_dwordx4 v[184:187], v[192:193], off offset:2048
	global_load_dwordx4 v[188:191], v[194:195], off offset:2048
	s_movk_i32 s18, 0xa00
	v_mov_b32_e32 v180, 0x800
	v_mov_b32_e32 v197, 0
	v_mov_b32_e32 v198, 0
	v_mov_b32_e32 v199, 0
	ds_write_b128 v78, v[196:199] offset:2176
	ds_write_b128 v78, v[196:199] offset:3264
	ds_write_b128 v78, v[196:199] offset:4352
	ds_write_b128 v78, v[196:199] offset:5440
	ds_write_b128 v78, v[196:199] offset:6528
	ds_write_b128 v78, v[196:199] offset:7616
	s_waitcnt vmcnt(9)
	v_cndmask_b32_e64 v66, v66, 0, s[8:9]
	v_cndmask_b32_e64 v67, v67, 0, s[8:9]
	v_cndmask_b32_e64 v68, v68, 0, s[8:9]
	v_cndmask_b32_e64 v69, v69, 0, s[8:9]
	s_waitcnt vmcnt(8)
	v_cndmask_b32_e64 v112, v112, 0, s[8:9]
	v_cndmask_b32_e64 v113, v113, 0, s[8:9]
	v_cndmask_b32_e64 v114, v114, 0, s[8:9]
	v_cndmask_b32_e64 v115, v115, 0, s[8:9]
	s_waitcnt vmcnt(7)
	v_cndmask_b32_e64 v104, v104, 0, s[8:9]
	v_cndmask_b32_e64 v105, v105, 0, s[8:9]
	v_cndmask_b32_e64 v106, v106, 0, s[8:9]
	v_cndmask_b32_e64 v107, v107, 0, s[8:9]
	s_waitcnt vmcnt(6)
	v_cndmask_b32_e64 v96, v96, 0, s[8:9]
	v_cndmask_b32_e64 v97, v97, 0, s[8:9]
	v_cndmask_b32_e64 v98, v98, 0, s[8:9]
	v_cndmask_b32_e64 v99, v99, 0, s[8:9]
	s_waitcnt vmcnt(5)
	v_cndmask_b32_e64 v100, v100, 0, s[8:9]
	v_cndmask_b32_e64 v101, v101, 0, s[8:9]
	v_cndmask_b32_e64 v102, v102, 0, s[8:9]
	v_cndmask_b32_e64 v103, v103, 0, s[8:9]
	s_waitcnt vmcnt(4)
	v_cndmask_b32_e64 v92, v92, 0, s[8:9]
	v_cndmask_b32_e64 v93, v93, 0, s[8:9]
	v_cndmask_b32_e64 v94, v94, 0, s[8:9]
	v_cndmask_b32_e64 v95, v95, 0, s[8:9]
	s_waitcnt vmcnt(3)
	v_cndmask_b32_e64 v88, v88, 0, s[8:9]
	v_cndmask_b32_e64 v89, v89, 0, s[8:9]
	v_cndmask_b32_e64 v90, v90, 0, s[8:9]
	v_cndmask_b32_e64 v91, v91, 0, s[8:9]
	s_waitcnt vmcnt(2)
	v_cndmask_b32_e64 v84, v84, 0, s[8:9]
	v_cndmask_b32_e64 v85, v85, 0, s[8:9]
	v_cndmask_b32_e64 v86, v86, 0, s[8:9]
	v_cndmask_b32_e64 v87, v87, 0, s[8:9]
	s_waitcnt vmcnt(1)
	ds_write_b128 v78, v[184:187]
	s_waitcnt vmcnt(0)
	ds_write_b128 v78, v[188:191] offset:1088
	v_mfma_f32_32x32x16_bf16 v[66:81], v[66:69], v[152:155], 0
	v_mfma_f32_32x32x16_bf16 v[66:81], v[112:115], v[144:147], v[66:81]
	v_mfma_f32_32x32x16_bf16 v[66:81], v[104:107], v[140:143], v[66:81]
	v_mfma_f32_32x32x16_bf16 v[66:81], v[96:99], v[132:135], v[66:81]
	v_mfma_f32_32x32x16_bf16 v[66:81], v[100:103], v[128:131], v[66:81]
	v_mfma_f32_32x32x16_bf16 v[66:81], v[92:95], v[120:123], v[66:81]
	v_mfma_f32_32x32x16_bf16 v[66:81], v[88:91], v[116:119], v[66:81]
	v_mfma_f32_32x32x16_bf16 v[66:81], v[84:87], v[108:111], v[66:81]
	v_mov_b32_e32 v84, 0
	v_mov_b32_e32 v85, v84
	v_mov_b32_e32 v86, v84
	v_mov_b32_e32 v87, v84
	v_mov_b32_e32 v88, v84
	v_mov_b32_e32 v89, v84
	v_mov_b32_e32 v90, v84
	v_mov_b32_e32 v91, v84
	v_mov_b32_e32 v92, v84
	v_mov_b32_e32 v93, v84
	v_mov_b32_e32 v94, v84
	v_mov_b32_e32 v95, v84
	v_mov_b32_e32 v96, v84
	v_mov_b32_e32 v97, v84
	v_mov_b32_e32 v98, v84
	v_mov_b32_e32 v99, v84
	v_mov_b32_e32 v100, v84
	v_mov_b32_e32 v101, v84
	v_mov_b32_e32 v102, v84
	v_mov_b32_e32 v103, v84
	v_mov_b32_e32 v104, v84
	v_mov_b32_e32 v105, v84
	v_mov_b32_e32 v106, v84
	v_mov_b32_e32 v107, v84
	v_mov_b32_e32 v112, v84
	v_mov_b32_e32 v113, v84
	v_mov_b32_e32 v114, v84
	v_mov_b32_e32 v115, v84
	v_mov_b32_e32 v124, v84
	v_mov_b32_e32 v125, v84
	v_mov_b32_e32 v126, v84
	v_mov_b32_e32 v127, v84
	v_mov_b32_e32 v136, v84
	v_mov_b32_e32 v137, v84
	v_mov_b32_e32 v138, v84
	v_mov_b32_e32 v139, v84
	v_mov_b32_e32 v148, v84
	v_mov_b32_e32 v149, v84
	v_mov_b32_e32 v150, v84
	v_mov_b32_e32 v151, v84
	v_mov_b32_e32 v156, v84
	v_mov_b32_e32 v157, v84
	v_mov_b32_e32 v158, v84
	v_mov_b32_e32 v159, v84
	v_mov_b32_e32 v160, v84
	v_mov_b32_e32 v161, v84
	v_mov_b32_e32 v162, v84
	v_mov_b32_e32 v163, v84
	v_mov_b32_e32 v164, v84
	v_mov_b32_e32 v165, v84
	v_mov_b32_e32 v166, v84
	v_mov_b32_e32 v167, v84
	v_mov_b32_e32 v168, v84
	v_mov_b32_e32 v169, v84
	v_mov_b32_e32 v170, v84
	v_mov_b32_e32 v171, v84
	v_mov_b32_e32 v172, v84
	v_mov_b32_e32 v173, v84
	v_mov_b32_e32 v174, v84
	v_mov_b32_e32 v175, v84
	v_mov_b32_e32 v176, v84
	v_mov_b32_e32 v177, v84
	v_mov_b32_e32 v178, v84
	v_mov_b32_e32 v179, v84

.LBB0_1004:
	s_or_b64 exec, exec, s[10:11]
	s_lshl_b64 s[26:27], s[16:17], 15
	s_add_u32 s10, s12, s26
	v_lshlrev_b32_e32 v50, 11, v12
	s_addc_u32 s11, s13, s27
	v_ashrrev_i32_e32 v51, 31, v50
	v_lshl_add_u64 v[48:49], s[10:11], 0, v[82:83]
	s_waitcnt lgkmcnt(1)
	v_lshlrev_b64 v[4:5], 2, v[50:51]
	s_waitcnt lgkmcnt(0)
	v_lshl_add_u64 v[6:7], v[48:49], 0, v[4:5]
	s_barrier
	v_mov_b32_e32 v218, 0x1000
	v_mov_b32_e32 v219, 0
	v_lshl_add_u64 v[216:217], v[6:7], 0, v[218:219]
	global_load_dword v200, v[6:7], off
	global_load_dword v201, v[6:7], off offset:512
	global_load_dword v202, v[6:7], off offset:1024
	global_load_dword v203, v[6:7], off offset:1536
	global_load_dword v204, v[6:7], off offset:2048
	global_load_dword v205, v[6:7], off offset:2560
	global_load_dword v206, v[6:7], off offset:3072
	global_load_dword v207, v[6:7], off offset:3584
	global_load_dword v208, v[216:217], off
	global_load_dword v209, v[216:217], off offset:512
	global_load_dword v210, v[216:217], off offset:1024
	global_load_dword v211, v[216:217], off offset:1536
	global_load_dword v212, v[216:217], off offset:2048
	global_load_dword v213, v[216:217], off offset:2560
	global_load_dword v214, v[216:217], off offset:3072
	v_mad_u64_u32 v[30:31], s[10:11], v12, 60, v[2:3]
	ds_read_b32 v51, v83 offset:8572
	v_readlane_b32 s10, v254, 53
	v_readlane_b32 s11, v254, 54
	ds_read_b128 v[6:9], v30 offset:8704
	ds_read_b128 v[10:13], v30 offset:8960
	ds_read_b128 v[14:17], v30 offset:9216
	ds_read_b128 v[18:21], v30 offset:9472
	ds_read_b128 v[22:25], v30 offset:9728
	ds_read_b128 v[26:29], v30 offset:9984
	ds_read_b128 v[62:65], v30 offset:10240
	ds_read_b128 v[66:69], v30 offset:10496
	s_lshl_b64 s[10:11], s[10:11], 2
	s_add_u32 s21, s24, s10
	s_waitcnt lgkmcnt(7)
	v_mul_f32_e32 v6, v46, v6
	s_addc_u32 s25, s25, s11
	s_add_u32 s10, s88, 0x1b81e000
	s_addc_u32 s11, s89, 0
	s_add_u32 s12, s80, s26
	s_addc_u32 s13, s81, s27
	v_or_b32_e32 v2, 0x80, v50
	s_lshl_b32 s24, s20, 2
	v_lshl_add_u64 v[52:53], s[12:13], 0, v[82:83]
	s_mov_b64 s[12:13], 0x6697040
	v_ashrrev_i32_e32 v3, 31, v2
	s_add_u32 s24, s21, s24
	v_lshl_add_u64 v[52:53], v[52:53], 0, s[12:13]
	v_lshlrev_b64 v[2:3], 2, v[2:3]
	s_addc_u32 s25, s25, 0
	v_lshl_add_u64 v[4:5], v[52:53], 0, v[4:5]
	v_lshl_add_u64 v[32:33], v[48:49], 0, v[2:3]
	global_load_dword v61, v82, s[24:25]
	v_mul_f32_e32 v7, v46, v7
	v_lshl_add_u64 v[2:3], v[52:53], 0, v[2:3]
	v_mul_f32_e32 v8, v46, v8
	v_mul_f32_e32 v9, v46, v9
	v_or_b32_e32 v54, 0x480, v50
	v_ashrrev_i32_e32 v55, 31, v54
	v_lshlrev_b64 v[54:55], 2, v[54:55]
	s_lshl_b32 s70, s20, 1
	s_waitcnt vmcnt(1)
	v_fmac_f32_e32 v6, v51, v200
	s_waitcnt lgkmcnt(6)
	v_fmac_f32_e32 v6, v47, v10
	s_waitcnt lgkmcnt(5)
	v_fmac_f32_e32 v6, v44, v14
	s_waitcnt lgkmcnt(4)
	v_fmac_f32_e32 v6, v45, v18
	s_waitcnt lgkmcnt(3)
	v_fmac_f32_e32 v6, v42, v22
	s_waitcnt lgkmcnt(2)
	v_fmac_f32_e32 v6, v43, v26
	s_waitcnt lgkmcnt(1)
	v_fmac_f32_e32 v6, v40, v62
	s_waitcnt lgkmcnt(0)
	v_fmac_f32_e32 v6, v41, v66
	global_store_dword v[4:5], v6, off
	v_or_b32_e32 v4, 0x100, v50
	v_ashrrev_i32_e32 v5, 31, v4
	v_lshlrev_b64 v[4:5], 2, v[4:5]
	v_lshl_add_u64 v[32:33], v[48:49], 0, v[4:5]
	v_lshl_add_u64 v[4:5], v[52:53], 0, v[4:5]
	s_waitcnt vmcnt(15)
	v_fmac_f32_e32 v7, v51, v201
	v_fmac_f32_e32 v7, v47, v11
	v_fmac_f32_e32 v7, v44, v15
	v_fmac_f32_e32 v7, v45, v19
	v_fmac_f32_e32 v7, v42, v23
	v_fmac_f32_e32 v7, v43, v27
	v_fmac_f32_e32 v7, v40, v63
	v_fmac_f32_e32 v7, v41, v67
	global_store_dword v[2:3], v7, off
	v_or_b32_e32 v2, 0x180, v50
	v_ashrrev_i32_e32 v3, 31, v2
	v_lshlrev_b64 v[6:7], 2, v[2:3]
	v_lshl_add_u64 v[2:3], v[48:49], 0, v[6:7]
	v_lshl_add_u64 v[6:7], v[52:53], 0, v[6:7]
	s_waitcnt vmcnt(15)
	v_fmac_f32_e32 v8, v51, v202
	v_fmac_f32_e32 v8, v47, v12
	v_fmac_f32_e32 v8, v44, v16
	v_fmac_f32_e32 v8, v45, v20
	v_fmac_f32_e32 v8, v42, v24
	v_fmac_f32_e32 v8, v43, v28
	v_fmac_f32_e32 v8, v40, v64
	v_fmac_f32_e32 v8, v41, v68
	global_store_dword v[4:5], v8, off
	v_or_b32_e32 v2, 0x200, v50
	v_ashrrev_i32_e32 v3, 31, v2
	v_lshlrev_b64 v[2:3], 2, v[2:3]
	v_lshl_add_u64 v[4:5], v[48:49], 0, v[2:3]
	v_or_b32_e32 v28, 0x280, v50
	v_lshl_add_u64 v[2:3], v[52:53], 0, v[2:3]
	s_waitcnt vmcnt(15)
	v_fmac_f32_e32 v9, v51, v203
	v_fmac_f32_e32 v9, v47, v13
	v_fmac_f32_e32 v9, v44, v17
	v_fmac_f32_e32 v9, v45, v21
	v_fmac_f32_e32 v9, v42, v25
	v_fmac_f32_e32 v9, v43, v29
	v_fmac_f32_e32 v9, v40, v65
	v_fmac_f32_e32 v9, v41, v69
	global_store_dword v[6:7], v9, off
	ds_read_b128 v[4:7], v30 offset:8720
	ds_read_b128 v[8:11], v30 offset:8976
	ds_read_b128 v[12:15], v30 offset:9232
	ds_read_b128 v[16:19], v30 offset:9488
	ds_read_b128 v[20:23], v30 offset:9744
	ds_read_b128 v[24:27], v30 offset:10000
	ds_read_b128 v[62:65], v30 offset:10256
	ds_read_b128 v[66:69], v30 offset:10512
	s_waitcnt lgkmcnt(7)
	v_mul_f32_e32 v4, v46, v4
	v_ashrrev_i32_e32 v29, 31, v28
	v_lshlrev_b64 v[28:29], 2, v[28:29]
	v_lshl_add_u64 v[32:33], v[48:49], 0, v[28:29]
	v_mul_f32_e32 v6, v46, v6
	v_mul_f32_e32 v7, v46, v7
	s_waitcnt vmcnt(15)
	v_fmac_f32_e32 v4, v51, v204
	s_waitcnt lgkmcnt(6)
	v_fmac_f32_e32 v4, v47, v8
	s_waitcnt lgkmcnt(5)
	v_fmac_f32_e32 v4, v44, v12
	s_waitcnt lgkmcnt(4)
	v_fmac_f32_e32 v4, v45, v16
	s_waitcnt lgkmcnt(3)
	v_fmac_f32_e32 v4, v42, v20
	s_waitcnt lgkmcnt(2)
	v_fmac_f32_e32 v4, v43, v24
	s_waitcnt lgkmcnt(1)
	v_fmac_f32_e32 v4, v40, v62
	s_waitcnt lgkmcnt(0)
	v_fmac_f32_e32 v4, v41, v66
	global_store_dword v[2:3], v4, off
	v_mul_f32_e32 v12, v46, v5
	v_or_b32_e32 v2, 0x300, v50
	v_ashrrev_i32_e32 v3, 31, v2
	v_lshlrev_b64 v[2:3], 2, v[2:3]
	v_lshl_add_u64 v[4:5], v[52:53], 0, v[28:29]
	v_lshl_add_u64 v[32:33], v[48:49], 0, v[2:3]
	v_lshl_add_u64 v[2:3], v[52:53], 0, v[2:3]
	s_waitcnt vmcnt(15)
	v_fmac_f32_e32 v12, v51, v205
	v_fmac_f32_e32 v12, v47, v9
	v_fmac_f32_e32 v12, v44, v13
	v_fmac_f32_e32 v12, v45, v17
	v_fmac_f32_e32 v12, v42, v21
	v_fmac_f32_e32 v12, v43, v25
	v_fmac_f32_e32 v12, v40, v63
	v_fmac_f32_e32 v12, v41, v67
	global_store_dword v[4:5], v12, off
	v_or_b32_e32 v4, 0x380, v50
	v_ashrrev_i32_e32 v5, 31, v4
	v_lshlrev_b64 v[4:5], 2, v[4:5]
	v_lshl_add_u64 v[8:9], v[48:49], 0, v[4:5]
	v_lshl_add_u64 v[4:5], v[52:53], 0, v[4:5]
	v_lshl_add_u64 v[66:67], v[48:49], 0, v[54:55]
	s_waitcnt vmcnt(15)
	v_fmac_f32_e32 v6, v51, v206
	v_fmac_f32_e32 v6, v47, v10
	v_fmac_f32_e32 v6, v44, v14
	v_fmac_f32_e32 v6, v45, v18
	v_fmac_f32_e32 v6, v42, v22
	v_fmac_f32_e32 v6, v43, v26
	v_fmac_f32_e32 v6, v40, v64
	v_fmac_f32_e32 v6, v41, v68
	global_store_dword v[2:3], v6, off
	v_or_b32_e32 v2, 0x400, v50
	v_ashrrev_i32_e32 v3, 31, v2
	v_lshlrev_b64 v[32:33], 2, v[2:3]
	v_lshl_add_u64 v[2:3], v[48:49], 0, v[32:33]
	v_lshl_add_u64 v[32:33], v[52:53], 0, v[32:33]
	s_waitcnt vmcnt(15)
	v_fmac_f32_e32 v7, v51, v207
	v_fmac_f32_e32 v7, v47, v11
	v_fmac_f32_e32 v7, v44, v15
	v_fmac_f32_e32 v7, v45, v19
	v_fmac_f32_e32 v7, v42, v23
	v_fmac_f32_e32 v7, v43, v27
	v_fmac_f32_e32 v7, v40, v65
	v_fmac_f32_e32 v7, v41, v69
	global_store_dword v[4:5], v7, off
	ds_read_b128 v[2:5], v30 offset:10528
	ds_read_b128 v[6:9], v30 offset:8736
	ds_read_b128 v[10:13], v30 offset:8992
	ds_read_b128 v[14:17], v30 offset:9248
	ds_read_b128 v[18:21], v30 offset:9504
	ds_read_b128 v[22:25], v30 offset:9760
	ds_read_b128 v[26:29], v30 offset:10016
	ds_read_b128 v[62:65], v30 offset:10272
	s_waitcnt lgkmcnt(6)
	v_mul_f32_e32 v6, v46, v6
	v_mul_f32_e32 v8, v46, v8
	s_waitcnt vmcnt(15)
	v_fmac_f32_e32 v6, v51, v208
	s_waitcnt lgkmcnt(5)
	v_fmac_f32_e32 v6, v47, v10
	s_waitcnt lgkmcnt(4)
	v_fmac_f32_e32 v6, v44, v14
	s_waitcnt lgkmcnt(3)
	v_fmac_f32_e32 v6, v45, v18
	s_waitcnt lgkmcnt(2)
	v_fmac_f32_e32 v6, v42, v22
	s_waitcnt lgkmcnt(1)
	v_fmac_f32_e32 v6, v43, v26
	s_waitcnt lgkmcnt(0)
	v_fmac_f32_e32 v6, v40, v62
	v_fmac_f32_e32 v6, v41, v2
	global_store_dword v[32:33], v6, off
	v_mul_f32_e32 v6, v46, v7
	v_lshl_add_u64 v[32:33], v[52:53], 0, v[54:55]
	v_or_b32_e32 v54, 0x500, v50
	v_ashrrev_i32_e32 v55, 31, v54
	v_lshlrev_b64 v[54:55], 2, v[54:55]
	v_lshl_add_u64 v[66:67], v[48:49], 0, v[54:55]
	v_or_b32_e32 v62, 0x680, v50
	s_waitcnt vmcnt(15)
	v_fmac_f32_e32 v6, v51, v209
	v_fmac_f32_e32 v6, v47, v11
	v_fmac_f32_e32 v6, v44, v15
	v_fmac_f32_e32 v6, v45, v19
	v_fmac_f32_e32 v6, v42, v23
	v_fmac_f32_e32 v6, v43, v27
	v_fmac_f32_e32 v6, v40, v63
	v_fmac_f32_e32 v6, v41, v3
	global_store_dword v[32:33], v6, off
	v_or_b32_e32 v6, 0x580, v50
	v_ashrrev_i32_e32 v7, 31, v6
	v_lshl_add_u64 v[2:3], v[52:53], 0, v[54:55]
	v_lshlrev_b64 v[6:7], 2, v[6:7]
	v_lshl_add_u64 v[10:11], v[48:49], 0, v[6:7]
	v_ashrrev_i32_e32 v63, 31, v62
	v_lshlrev_b64 v[62:63], 2, v[62:63]
	s_waitcnt vmcnt(15)
	v_fmac_f32_e32 v8, v51, v210
	v_fmac_f32_e32 v8, v47, v12
	v_fmac_f32_e32 v8, v44, v16
	v_fmac_f32_e32 v8, v45, v20
	v_fmac_f32_e32 v8, v42, v24
	v_fmac_f32_e32 v8, v43, v28
	v_fmac_f32_e32 v8, v40, v64
	v_fmac_f32_e32 v8, v41, v4
	global_store_dword v[2:3], v8, off
	v_mul_f32_e32 v8, v46, v9
	v_lshl_add_u64 v[2:3], v[52:53], 0, v[6:7]
	v_or_b32_e32 v6, 0x600, v50
	v_ashrrev_i32_e32 v7, 31, v6
	v_lshlrev_b64 v[54:55], 2, v[6:7]
	v_lshl_add_u64 v[6:7], v[48:49], 0, v[54:55]
	v_lshl_add_u64 v[54:55], v[52:53], 0, v[54:55]
	s_waitcnt vmcnt(15)
	v_fmac_f32_e32 v8, v51, v211
	v_fmac_f32_e32 v8, v47, v13
	v_fmac_f32_e32 v8, v44, v17
	v_fmac_f32_e32 v8, v45, v21
	v_fmac_f32_e32 v8, v42, v25
	v_fmac_f32_e32 v8, v43, v29
	v_fmac_f32_e32 v8, v40, v65
	v_fmac_f32_e32 v8, v41, v5
	global_store_dword v[2:3], v8, off
	ds_read_b128 v[6:9], v30 offset:8752
	ds_read_b128 v[2:5], v30 offset:9008
	ds_read_b128 v[10:13], v30 offset:9264
	ds_read_b128 v[14:17], v30 offset:9520
	ds_read_b128 v[18:21], v30 offset:9776
	ds_read_b128 v[22:25], v30 offset:10032
	ds_read_b128 v[26:29], v30 offset:10288
	ds_read_b128 v[30:33], v30 offset:10544
	s_waitcnt lgkmcnt(7)
	v_mul_f32_e32 v6, v46, v6
	v_lshl_add_u64 v[64:65], v[48:49], 0, v[62:63]
	v_mul_f32_e32 v8, v46, v8
	s_waitcnt vmcnt(15)
	v_fmac_f32_e32 v6, v51, v212
	s_waitcnt lgkmcnt(6)
	v_fmac_f32_e32 v6, v47, v2
	s_waitcnt lgkmcnt(5)
	v_fmac_f32_e32 v6, v44, v10
	s_waitcnt lgkmcnt(4)
	v_fmac_f32_e32 v6, v45, v14
	s_waitcnt lgkmcnt(3)
	v_fmac_f32_e32 v6, v42, v18
	s_waitcnt lgkmcnt(2)
	v_fmac_f32_e32 v6, v43, v22
	s_waitcnt lgkmcnt(1)
	v_fmac_f32_e32 v6, v40, v26
	s_waitcnt lgkmcnt(0)
	v_fmac_f32_e32 v6, v41, v30
	global_store_dword v[54:55], v6, off
	v_mul_f32_e32 v6, v46, v7
	v_lshl_add_u64 v[54:55], v[52:53], 0, v[62:63]
	v_or_b32_e32 v62, 0x700, v50
	v_ashrrev_i32_e32 v63, 31, v62
	v_lshlrev_b64 v[62:63], 2, v[62:63]
	v_lshl_add_u64 v[64:65], v[48:49], 0, v[62:63]
	v_add_u32_e32 v18, 0, v60
	v_mov_b32_e32 v35, v83
	v_or_b32_e32 v26, 0x780, v50
	s_waitcnt vmcnt(15)
	v_fmac_f32_e32 v6, v51, v213
	v_fmac_f32_e32 v6, v47, v3
	v_fmac_f32_e32 v6, v44, v11
	v_fmac_f32_e32 v6, v45, v15
	v_fmac_f32_e32 v6, v42, v19
	v_fmac_f32_e32 v6, v43, v23
	v_fmac_f32_e32 v6, v40, v27
	v_fmac_f32_e32 v6, v41, v31
	global_store_dword v[54:55], v6, off
	ds_read_b64 v[18:19], v18 offset:8640
	v_add_u32_e32 v6, 4, v36
	v_lshl_add_u64 v[2:3], v[38:39], 0, s[70:71]
	v_ashrrev_i32_e32 v7, 31, v6
	v_mov_b64_e32 v[10:11], s[18:19]
	v_add_u32_e32 v27, 0, v59
	v_lshl_add_u64 v[2:3], v[2:3], 0, v[34:35]
	v_mad_i64_i32 v[10:11], s[12:13], v6, s83, v[10:11]
	v_lshlrev_b64 v[14:15], 12, v[36:37]
	v_lshlrev_b64 v[6:7], 12, v[6:7]
	ds_read_b64 v[30:31], v27 offset:8640
	s_waitcnt lgkmcnt(1)
	v_add_f32_e32 v18, v18, v19
	v_lshl_add_u64 v[14:15], s[10:11], 0, v[14:15]
	v_lshl_add_u64 v[6:7], s[10:11], 0, v[6:7]
	v_fmamk_f32 v18, v18, 0x3c000000, v245
	s_mov_b32 s12, 0xf800000
	v_add_co_u32_e64 v2, s[10:11], s82, v2
	v_mul_f32_e32 v19, 0x4f800000, v18
	v_cmp_gt_f32_e32 vcc, s12, v18
	v_addc_co_u32_e64 v3, s[10:11], 0, v3, s[10:11]
	s_nop 0
	v_cndmask_b32_e32 v18, v18, v19, vcc
	global_load_ushort v19, v[2:3], off
	v_lshl_add_u64 v[10:11], v[10:11], 0, s[70:71]
	v_lshl_add_u64 v[10:11], v[10:11], 0, v[34:35]
	v_add_co_u32_e64 v2, s[10:11], s82, v10
	v_ashrrev_i32_e32 v27, 31, v26
	s_nop 0
	v_addc_co_u32_e64 v3, s[10:11], 0, v11, s[10:11]
	global_load_ushort v36, v[2:3], off
	v_lshl_add_u64 v[22:23], v[52:53], 0, v[62:63]
	v_lshlrev_b64 v[2:3], 2, v[26:27]
	v_lshl_add_u64 v[10:11], v[48:49], 0, v[2:3]
	v_sqrt_f32_e32 v37, v18
	v_lshl_add_u64 v[14:15], v[14:15], 0, s[70:71]
	v_lshl_add_u64 v[14:15], v[14:15], 0, v[34:35]
	v_lshl_add_u64 v[6:7], v[6:7], 0, s[70:71]
	v_add_u32_e32 v26, -1, v37
	v_fma_f32 v27, -v26, v37, v18
	v_cmp_ge_f32_e64 s[10:11], 0, v27
	v_add_u32_e32 v27, 1, v37
	v_lshl_add_u64 v[6:7], v[6:7], 0, v[34:35]
	v_cndmask_b32_e64 v26, v37, v26, s[10:11]
	v_lshl_add_u64 v[2:3], v[52:53], 0, v[2:3]
	s_waitcnt vmcnt(2)
	v_fmac_f32_e32 v8, v51, v214
	v_fmac_f32_e32 v8, v47, v4
	v_fmac_f32_e32 v8, v44, v12
	v_fmac_f32_e32 v8, v45, v16
	v_fmac_f32_e32 v8, v42, v20
	v_fmac_f32_e32 v8, v43, v24
	v_fmac_f32_e32 v8, v40, v28
	v_fmac_f32_e32 v8, v41, v32
	global_store_dword v[22:23], v8, off
	global_load_dword v4, v[10:11], off
	v_fma_f32 v8, -v27, v37, v18
	v_cmp_lt_f32_e64 s[10:11], 0, v8
	s_nop 1
	v_cndmask_b32_e64 v8, v26, v27, s[10:11]
	v_mul_f32_e32 v10, 0x37800000, v8
	v_cndmask_b32_e32 v8, v8, v10, vcc
	v_cmp_class_f32_e32 vcc, v18, v251
	s_nop 1
	v_cndmask_b32_e32 v8, v8, v18, vcc
	v_div_scale_f32 v10, s[10:11], v8, v8, 1.0
	v_rcp_f32_e32 v11, v10
	s_waitcnt lgkmcnt(0)
	v_add_f32_e32 v18, v30, v31
	v_fmamk_f32 v18, v18, 0x3c000000, v245
	v_mul_f32_e32 v20, 0x4f800000, v18
	v_cmp_gt_f32_e64 s[10:11], s12, v18
	v_fma_f32 v12, -v10, v11, 1.0
	v_fmac_f32_e32 v11, v12, v11
	v_cndmask_b32_e64 v18, v18, v20, s[10:11]
	v_div_scale_f32 v12, vcc, 1.0, v8, 1.0
	v_sqrt_f32_e32 v20, v18
	v_mul_f32_e32 v16, v12, v11
	v_fma_f32 v22, -v10, v16, v12
	v_fmac_f32_e32 v16, v22, v11
	v_fma_f32 v10, -v10, v16, v12
	v_add_u32_e32 v12, -1, v20
	v_fma_f32 v22, -v12, v20, v18
	v_cmp_ge_f32_e64 s[12:13], 0, v22
	v_add_u32_e32 v22, 1, v20
	v_div_fmas_f32 v10, v10, v11, v16
	v_cndmask_b32_e64 v12, v20, v12, s[12:13]
	v_fma_f32 v20, -v22, v20, v18
	v_cmp_lt_f32_e64 s[12:13], 0, v20
	v_div_fixup_f32 v8, v10, v8, 1.0
	v_mul_f32_e32 v8, v58, v8
	v_cndmask_b32_e64 v12, v12, v22, s[12:13]
	v_mul_f32_e32 v20, 0x37800000, v12
	v_cndmask_b32_e64 v12, v12, v20, s[10:11]
	v_cmp_class_f32_e64 s[10:11], v18, v251
	v_mul_f32_e32 v8, v61, v8
	s_nop 0
	v_cndmask_b32_e64 v12, v12, v18, s[10:11]
	v_div_scale_f32 v18, s[10:11], v12, v12, 1.0
	v_rcp_f32_e32 v20, v18
	s_nop 0
	v_fma_f32 v10, -v18, v20, 1.0
	v_fmac_f32_e32 v20, v10, v20
	v_div_scale_f32 v10, vcc, 1.0, v12, 1.0
	v_mul_f32_e32 v11, v10, v20
	v_fma_f32 v16, -v18, v11, v10
	v_fmac_f32_e32 v11, v16, v20
	v_fma_f32 v10, -v18, v11, v10
	v_div_fmas_f32 v10, v10, v20, v11
	s_waitcnt vmcnt(3)
	v_lshlrev_b32_e32 v11, 16, v19
	v_mul_f32_e32 v11, 0xbfb8aa3b, v11
	v_exp_f32_e32 v11, v11
	v_div_fixup_f32 v10, v10, v12, 1.0
	s_waitcnt vmcnt(2)
	v_lshlrev_b32_e32 v12, 16, v36
	v_mul_f32_e32 v12, 0xbfb8aa3b, v12
	v_add_f32_e32 v11, 1.0, v11
	v_rcp_f32_e32 v11, v11
	v_exp_f32_e32 v12, v12
	v_mul_f32_e32 v8, v8, v11
	v_bfe_u32 v11, v8, 16, 1
	v_add3_u32 v8, v8, v11, s73
	v_add_f32_e32 v11, 1.0, v12
	v_rcp_f32_e32 v11, v11
	global_store_short_d16_hi v[14:15], v8, off
	v_mul_f32_e32 v8, v57, v10
	v_mul_f32_e32 v8, v61, v8
	v_mul_f32_e32 v8, v8, v11
	v_bfe_u32 v10, v8, 16, 1
	v_add3_u32 v8, v8, v10, s73
	global_store_short_d16_hi v[6:7], v8, off
	v_mul_f32_e32 v6, v46, v9
	s_waitcnt vmcnt(2)
	v_fmac_f32_e32 v6, v51, v4
	v_fmac_f32_e32 v6, v47, v5
	v_fmac_f32_e32 v6, v44, v13
	v_fmac_f32_e32 v6, v45, v17
	v_fmac_f32_e32 v6, v42, v21
	v_fmac_f32_e32 v6, v43, v25
	v_fmac_f32_e32 v6, v40, v29
	v_fmac_f32_e32 v6, v41, v33
	global_store_dword v[2:3], v6, off
	s_and_saveexec_b64 s[10:11], s[8:9]
	s_cbranch_execz .LBB0_1006
	v_ashrrev_i32_e32 v235, 31, v234
	v_lshlrev_b64 v[2:3], 2, v[234:235]
	v_lshl_add_u64 v[4:5], s[14:15], 0, v[2:3]
	global_load_dword v12, v[4:5], off
	ds_read2st64_b32 v[4:5], v56 offset0:34 offset1:35
	ds_read2st64_b32 v[6:7], v56 offset0:36 offset1:37
	ds_read2st64_b32 v[8:9], v56 offset0:38 offset1:39
	ds_read2st64_b32 v[10:11], v56 offset0:40 offset1:41
	s_lshl_b64 s[8:9], s[22:23], 2
	s_add_u32 s8, s80, s8
	s_addc_u32 s9, s81, s9
	v_lshl_add_u64 v[2:3], s[8:9], 0, v[2:3]
	v_add_co_u32_e32 v2, vcc, 0x7697000, v2
	s_waitcnt vmcnt(0) lgkmcnt(3)
	v_fma_f32 v4, v51, v12, v4
	v_add_f32_e32 v4, v4, v5
	s_waitcnt lgkmcnt(2)
	v_add_f32_e32 v4, v4, v6
	v_add_f32_e32 v4, v4, v7
	s_waitcnt lgkmcnt(1)
	v_add_f32_e32 v4, v4, v8
	v_add_f32_e32 v4, v4, v9
	s_waitcnt lgkmcnt(0)
	v_add_f32_e32 v4, v4, v10
	v_add_f32_e32 v4, v4, v11
	v_addc_co_u32_e32 v3, vcc, 0, v3, vcc
	global_store_dword v[2:3], v4, off offset:64
